# GEMM K-loops: removed the redundant second lgkmcnt(0) at the head of each MFMA block
# baseline (speedup 1.0000x reference)
.LBB0_129:
	s_add_u32 s44, s80, 0xfffc0080
	s_addc_u32 s45, s81, -1
	s_add_i32 s88, 0, 0x10000
	s_cmp_eq_u32 s87, 12
	s_cselect_b32 s85, s30, s45
	s_cselect_b32 s84, s47, s44
	v_add_u32_e32 v0, s88, v233
	s_cselect_b32 s83, s49, s86
	s_cselect_b32 s82, s71, s73
	s_add_i32 s89, 0, 0x14000
	ds_read_b128 v[148:151], v0
	ds_read_b128 v[152:155], v0 offset:1024
	ds_read_b128 v[156:159], v0 offset:2048
	ds_read_b128 v[160:163], v0 offset:3072
	v_add_u32_e32 v0, s89, v233
	s_waitcnt lgkmcnt(0)
	ds_read_b128 v[132:135], v0
	ds_read_b128 v[136:139], v0 offset:1024
	ds_read_b128 v[140:143], v0 offset:2048
	ds_read_b128 v[144:147], v0 offset:3072
	v_lshl_add_u64 v[2:3], s[80:81], 0, v[214:215]
	s_add_i32 m0, s97, 0xc000
	ds_read_b128 v[164:167], v237
	ds_read_b128 v[168:171], v237 offset:1024
	ds_read_b128 v[172:175], v237 offset:2048
	ds_read_b128 v[176:179], v237 offset:3072
	ds_read_b128 v[180:183], v237 offset:4096
	ds_read_b128 v[184:187], v237 offset:5120
	ds_read_b128 v[188:191], v237 offset:6144
	ds_read_b128 v[192:195], v237 offset:7168
	global_load_lds_dwordx4 v[2:3], off
	v_lshl_add_u64 v[2:3], s[80:81], 0, v[216:217]
	s_add_i32 m0, s97, 0xe000
	s_nop 0
	global_load_lds_dwordx4 v[2:3], off
	s_waitcnt vmcnt(8)
	s_waitcnt lgkmcnt(0)
	s_barrier
	s_setprio 1
	v_mfma_f32_16x16x32_bf16 v[128:131], v[148:151], v[164:167], v[128:131]
	v_mfma_f32_16x16x32_bf16 v[120:123], v[156:159], v[164:167], v[120:123]
	v_mfma_f32_16x16x32_bf16 v[124:127], v[148:151], v[172:175], v[124:127]
	v_mfma_f32_16x16x32_bf16 v[116:119], v[156:159], v[172:175], v[116:119]
	v_mfma_f32_16x16x32_bf16 v[96:99], v[148:151], v[180:183], v[96:99]
	v_mfma_f32_16x16x32_bf16 v[88:91], v[156:159], v[180:183], v[88:91]
	v_mfma_f32_16x16x32_bf16 v[92:95], v[148:151], v[188:191], v[92:95]
	v_mfma_f32_16x16x32_bf16 v[84:87], v[156:159], v[188:191], v[84:87]
	v_mfma_f32_16x16x32_bf16 v[128:131], v[152:155], v[168:171], v[128:131]
	v_mfma_f32_16x16x32_bf16 v[120:123], v[160:163], v[168:171], v[120:123]
	v_mfma_f32_16x16x32_bf16 v[124:127], v[152:155], v[176:179], v[124:127]
	v_mfma_f32_16x16x32_bf16 v[116:119], v[160:163], v[176:179], v[116:119]
	v_mfma_f32_16x16x32_bf16 v[96:99], v[152:155], v[184:187], v[96:99]
	v_mfma_f32_16x16x32_bf16 v[88:91], v[160:163], v[184:187], v[88:91]
	v_mfma_f32_16x16x32_bf16 v[92:95], v[152:155], v[192:195], v[92:95]
	v_mfma_f32_16x16x32_bf16 v[84:87], v[160:163], v[192:195], v[84:87]
	v_mfma_f32_16x16x32_bf16 v[112:115], v[132:135], v[164:167], v[112:115]
	v_mfma_f32_16x16x32_bf16 v[104:107], v[140:143], v[164:167], v[104:107]
	v_mfma_f32_16x16x32_bf16 v[108:111], v[132:135], v[172:175], v[108:111]
	v_mfma_f32_16x16x32_bf16 v[100:103], v[140:143], v[172:175], v[100:103]
	v_mfma_f32_16x16x32_bf16 v[80:83], v[132:135], v[180:183], v[80:83]
	v_mfma_f32_16x16x32_bf16 v[72:75], v[140:143], v[180:183], v[72:75]
	v_mfma_f32_16x16x32_bf16 v[76:79], v[132:135], v[188:191], v[76:79]
	v_mfma_f32_16x16x32_bf16 v[68:71], v[140:143], v[188:191], v[68:71]
	v_mfma_f32_16x16x32_bf16 v[112:115], v[136:139], v[168:171], v[112:115]
	v_mfma_f32_16x16x32_bf16 v[104:107], v[144:147], v[168:171], v[104:107]
	v_mfma_f32_16x16x32_bf16 v[108:111], v[136:139], v[176:179], v[108:111]
	v_mfma_f32_16x16x32_bf16 v[100:103], v[144:147], v[176:179], v[100:103]
	v_mfma_f32_16x16x32_bf16 v[80:83], v[136:139], v[184:187], v[80:83]
	v_mfma_f32_16x16x32_bf16 v[72:75], v[144:147], v[184:187], v[72:75]
	v_mfma_f32_16x16x32_bf16 v[76:79], v[136:139], v[192:195], v[76:79]
	v_mfma_f32_16x16x32_bf16 v[68:71], v[144:147], v[192:195], v[68:71]
	s_setprio 0
	s_barrier
	s_add_i32 s44, s88, s96
	v_lshl_add_u64 v[2:3], s[82:83], 0, v[208:209]
	s_mov_b32 m0, s44
	ds_read_b128 v[188:191], v237 offset:16384
	ds_read_b128 v[192:195], v237 offset:17408
	ds_read_b128 v[180:183], v237 offset:18432
	ds_read_b128 v[184:187], v237 offset:19456
	ds_read_b128 v[172:175], v237 offset:20480
	ds_read_b128 v[176:179], v237 offset:21504
	ds_read_b128 v[164:167], v237 offset:22528
	ds_read_b128 v[168:171], v237 offset:23552
	global_load_lds_dwordx4 v[2:3], off
	s_add_i32 m0, s44, 0x2000
	s_add_u32 s44, s82, 0x40000
	v_lshl_add_u64 v[218:219], s[82:83], 0, v[212:213]
	s_addc_u32 s45, s83, 0
	s_add_i32 s88, s89, s96
	global_load_lds_dwordx4 v[218:219], off
	v_lshl_add_u64 v[220:221], s[44:45], 0, v[208:209]
	s_mov_b32 m0, s88
	v_lshl_add_u64 v[222:223], s[84:85], 0, v[210:211]
	global_load_lds_dwordx4 v[220:221], off
	v_lshl_add_u64 v[220:221], s[44:45], 0, v[212:213]
	s_add_i32 m0, s88, 0x2000
	v_cndmask_b32_e64 v0, 0, 1, s[50:51]
	global_load_lds_dwordx4 v[220:221], off
	v_lshl_add_u64 v[220:221], s[84:85], 0, v[206:207]
	s_mov_b32 m0, s97
	v_cmp_ne_u32_e64 s[44:45], 1, v0
	global_load_lds_dwordx4 v[220:221], off
	s_mov_b32 m0, s25
	s_andn2_b64 vcc, exec, s[50:51]
	global_load_lds_dwordx4 v[222:223], off
	s_waitcnt vmcnt(8)
	s_waitcnt lgkmcnt(0)
	s_barrier
	s_cbranch_vccnz .LBB0_131
	s_setprio 1
	v_mfma_f32_16x16x32_bf16 v[64:67], v[148:151], v[188:191], v[64:67]
	v_mfma_f32_16x16x32_bf16 v[56:59], v[156:159], v[188:191], v[56:59]
	v_mfma_f32_16x16x32_bf16 v[60:63], v[148:151], v[180:183], v[60:63]
	v_mfma_f32_16x16x32_bf16 v[52:55], v[156:159], v[180:183], v[52:55]
	v_mfma_f32_16x16x32_bf16 v[32:35], v[148:151], v[172:175], v[32:35]
	v_mfma_f32_16x16x32_bf16 v[24:27], v[156:159], v[172:175], v[24:27]
	v_mfma_f32_16x16x32_bf16 v[28:31], v[148:151], v[164:167], v[28:31]
	v_mfma_f32_16x16x32_bf16 v[20:23], v[156:159], v[164:167], v[20:23]
	v_mfma_f32_16x16x32_bf16 v[64:67], v[152:155], v[192:195], v[64:67]
	v_mfma_f32_16x16x32_bf16 v[56:59], v[160:163], v[192:195], v[56:59]
	v_mfma_f32_16x16x32_bf16 v[60:63], v[152:155], v[184:187], v[60:63]
	v_mfma_f32_16x16x32_bf16 v[52:55], v[160:163], v[184:187], v[52:55]
	v_mfma_f32_16x16x32_bf16 v[32:35], v[152:155], v[176:179], v[32:35]
	v_mfma_f32_16x16x32_bf16 v[24:27], v[160:163], v[176:179], v[24:27]
	v_mfma_f32_16x16x32_bf16 v[28:31], v[152:155], v[168:171], v[28:31]
	v_mfma_f32_16x16x32_bf16 v[20:23], v[160:163], v[168:171], v[20:23]
	v_mfma_f32_16x16x32_bf16 v[48:51], v[132:135], v[188:191], v[48:51]
	v_mfma_f32_16x16x32_bf16 v[40:43], v[140:143], v[188:191], v[40:43]
	v_mfma_f32_16x16x32_bf16 v[44:47], v[132:135], v[180:183], v[44:47]
	v_mfma_f32_16x16x32_bf16 v[36:39], v[140:143], v[180:183], v[36:39]
	v_mfma_f32_16x16x32_bf16 v[16:19], v[132:135], v[172:175], v[16:19]
	v_mfma_f32_16x16x32_bf16 v[8:11], v[140:143], v[172:175], v[8:11]
	v_mfma_f32_16x16x32_bf16 v[12:15], v[132:135], v[164:167], v[12:15]
	v_mfma_f32_16x16x32_bf16 v[4:7], v[140:143], v[164:167], v[4:7]
	v_mfma_f32_16x16x32_bf16 v[48:51], v[136:139], v[192:195], v[48:51]
	v_mfma_f32_16x16x32_bf16 v[40:43], v[144:147], v[192:195], v[40:43]
	v_mfma_f32_16x16x32_bf16 v[44:47], v[136:139], v[184:187], v[44:47]
	v_mfma_f32_16x16x32_bf16 v[36:39], v[144:147], v[184:187], v[36:39]
	v_mfma_f32_16x16x32_bf16 v[16:19], v[136:139], v[176:179], v[16:19]
	v_mfma_f32_16x16x32_bf16 v[8:11], v[144:147], v[176:179], v[8:11]
	v_mfma_f32_16x16x32_bf16 v[12:15], v[136:139], v[168:171], v[12:15]
	v_mfma_f32_16x16x32_bf16 v[4:7], v[144:147], v[168:171], v[4:7]
	s_setprio 0
.LBB0_131:
	s_barrier
	s_add_i32 s88, 0, 0x18000
	v_add_u32_e32 v0, s88, v233
	s_add_i32 s89, 0, 0x1c000
	ds_read_b128 v[148:151], v0
	ds_read_b128 v[152:155], v0 offset:1024
	ds_read_b128 v[156:159], v0 offset:2048
	ds_read_b128 v[160:163], v0 offset:3072
	v_add_u32_e32 v0, s89, v233
	ds_read_b128 v[132:135], v0
	ds_read_b128 v[136:139], v0 offset:1024
	ds_read_b128 v[140:143], v0 offset:2048
	ds_read_b128 v[144:147], v0 offset:3072
	s_add_u32 s84, s84, 0x40000
	s_addc_u32 s85, s85, 0
	s_mov_b32 m0, s55
	v_lshl_add_u64 v[238:239], s[84:85], 0, v[206:207]
	s_waitcnt lgkmcnt(0)
	ds_read_b128 v[164:167], v237 offset:32768
	ds_read_b128 v[168:171], v237 offset:33792
	ds_read_b128 v[172:175], v237 offset:34816
	ds_read_b128 v[176:179], v237 offset:35840
	ds_read_b128 v[180:183], v237 offset:36864
	ds_read_b128 v[184:187], v237 offset:37888
	ds_read_b128 v[188:191], v237 offset:38912
	ds_read_b128 v[192:195], v237 offset:39936
	global_load_lds_dwordx4 v[238:239], off
	v_lshl_add_u64 v[238:239], s[84:85], 0, v[210:211]
	s_mov_b32 m0, s92
	s_nop 0
	global_load_lds_dwordx4 v[238:239], off
	s_waitcnt vmcnt(8)
	s_waitcnt lgkmcnt(0)
	s_barrier
	s_setprio 1
	v_mfma_f32_16x16x32_bf16 v[128:131], v[148:151], v[164:167], v[128:131]
	v_mfma_f32_16x16x32_bf16 v[120:123], v[156:159], v[164:167], v[120:123]
	v_mfma_f32_16x16x32_bf16 v[124:127], v[148:151], v[172:175], v[124:127]
	v_mfma_f32_16x16x32_bf16 v[116:119], v[156:159], v[172:175], v[116:119]
	v_mfma_f32_16x16x32_bf16 v[96:99], v[148:151], v[180:183], v[96:99]
	v_mfma_f32_16x16x32_bf16 v[88:91], v[156:159], v[180:183], v[88:91]
	v_mfma_f32_16x16x32_bf16 v[92:95], v[148:151], v[188:191], v[92:95]
	v_mfma_f32_16x16x32_bf16 v[84:87], v[156:159], v[188:191], v[84:87]
	v_mfma_f32_16x16x32_bf16 v[128:131], v[152:155], v[168:171], v[128:131]
	v_mfma_f32_16x16x32_bf16 v[120:123], v[160:163], v[168:171], v[120:123]
	v_mfma_f32_16x16x32_bf16 v[124:127], v[152:155], v[176:179], v[124:127]
	v_mfma_f32_16x16x32_bf16 v[116:119], v[160:163], v[176:179], v[116:119]
	v_mfma_f32_16x16x32_bf16 v[96:99], v[152:155], v[184:187], v[96:99]
	v_mfma_f32_16x16x32_bf16 v[88:91], v[160:163], v[184:187], v[88:91]
	v_mfma_f32_16x16x32_bf16 v[92:95], v[152:155], v[192:195], v[92:95]
	v_mfma_f32_16x16x32_bf16 v[84:87], v[160:163], v[192:195], v[84:87]
	v_mfma_f32_16x16x32_bf16 v[112:115], v[132:135], v[164:167], v[112:115]
	v_mfma_f32_16x16x32_bf16 v[104:107], v[140:143], v[164:167], v[104:107]
	v_mfma_f32_16x16x32_bf16 v[108:111], v[132:135], v[172:175], v[108:111]
	v_mfma_f32_16x16x32_bf16 v[100:103], v[140:143], v[172:175], v[100:103]
	v_mfma_f32_16x16x32_bf16 v[80:83], v[132:135], v[180:183], v[80:83]
	v_mfma_f32_16x16x32_bf16 v[72:75], v[140:143], v[180:183], v[72:75]
	v_mfma_f32_16x16x32_bf16 v[76:79], v[132:135], v[188:191], v[76:79]
	v_mfma_f32_16x16x32_bf16 v[68:71], v[140:143], v[188:191], v[68:71]
	v_mfma_f32_16x16x32_bf16 v[112:115], v[136:139], v[168:171], v[112:115]
	v_mfma_f32_16x16x32_bf16 v[104:107], v[144:147], v[168:171], v[104:107]
	v_mfma_f32_16x16x32_bf16 v[108:111], v[136:139], v[176:179], v[108:111]
	v_mfma_f32_16x16x32_bf16 v[100:103], v[144:147], v[176:179], v[100:103]
	v_mfma_f32_16x16x32_bf16 v[80:83], v[136:139], v[184:187], v[80:83]
	v_mfma_f32_16x16x32_bf16 v[72:75], v[144:147], v[184:187], v[72:75]
	v_mfma_f32_16x16x32_bf16 v[76:79], v[136:139], v[192:195], v[76:79]
	v_mfma_f32_16x16x32_bf16 v[68:71], v[144:147], v[192:195], v[68:71]
	s_setprio 0
	s_barrier
	s_add_i32 s84, s88, s96
	v_lshl_add_u64 v[2:3], v[2:3], 0, s[58:59]
	s_mov_b32 m0, s84
	ds_read_b128 v[188:191], v237 offset:49152
	ds_read_b128 v[192:195], v237 offset:50176
	ds_read_b128 v[180:183], v237 offset:51200
	ds_read_b128 v[184:187], v237 offset:52224
	ds_read_b128 v[172:175], v237 offset:53248
	ds_read_b128 v[176:179], v237 offset:54272
	ds_read_b128 v[164:167], v237 offset:55296
	ds_read_b128 v[168:171], v237 offset:56320
	global_load_lds_dwordx4 v[2:3], off
	s_add_i32 m0, s84, 0x2000
	s_add_u32 s82, s82, 0x40080
	v_lshl_add_u64 v[2:3], v[218:219], 0, s[58:59]
	s_addc_u32 s83, s83, 0
	s_add_i32 s84, s89, s96
	global_load_lds_dwordx4 v[2:3], off
	v_lshl_add_u64 v[2:3], s[82:83], 0, v[208:209]
	s_mov_b32 m0, s84
	s_and_b64 vcc, exec, s[44:45]
	global_load_lds_dwordx4 v[2:3], off
	v_lshl_add_u64 v[2:3], s[82:83], 0, v[212:213]
	s_add_i32 m0, s84, 0x2000
	s_nop 0
	global_load_lds_dwordx4 v[2:3], off
	v_lshl_add_u64 v[2:3], v[220:221], 0, s[58:59]
	s_mov_b32 m0, s61
	s_nop 0
	global_load_lds_dwordx4 v[2:3], off
	v_lshl_add_u64 v[2:3], v[222:223], 0, s[58:59]
	s_mov_b32 m0, s13
	s_nop 0
	global_load_lds_dwordx4 v[2:3], off
	s_waitcnt vmcnt(8)
	s_waitcnt lgkmcnt(0)
	s_barrier
	s_cbranch_vccnz .LBB0_128
	s_setprio 1
	v_mfma_f32_16x16x32_bf16 v[64:67], v[148:151], v[188:191], v[64:67]
	v_mfma_f32_16x16x32_bf16 v[56:59], v[156:159], v[188:191], v[56:59]
	v_mfma_f32_16x16x32_bf16 v[60:63], v[148:151], v[180:183], v[60:63]
	v_mfma_f32_16x16x32_bf16 v[52:55], v[156:159], v[180:183], v[52:55]
	v_mfma_f32_16x16x32_bf16 v[32:35], v[148:151], v[172:175], v[32:35]
	v_mfma_f32_16x16x32_bf16 v[24:27], v[156:159], v[172:175], v[24:27]
	v_mfma_f32_16x16x32_bf16 v[28:31], v[148:151], v[164:167], v[28:31]
	v_mfma_f32_16x16x32_bf16 v[20:23], v[156:159], v[164:167], v[20:23]
	v_mfma_f32_16x16x32_bf16 v[64:67], v[152:155], v[192:195], v[64:67]
	v_mfma_f32_16x16x32_bf16 v[56:59], v[160:163], v[192:195], v[56:59]
	v_mfma_f32_16x16x32_bf16 v[60:63], v[152:155], v[184:187], v[60:63]
	v_mfma_f32_16x16x32_bf16 v[52:55], v[160:163], v[184:187], v[52:55]
	v_mfma_f32_16x16x32_bf16 v[32:35], v[152:155], v[176:179], v[32:35]
	v_mfma_f32_16x16x32_bf16 v[24:27], v[160:163], v[176:179], v[24:27]
	v_mfma_f32_16x16x32_bf16 v[28:31], v[152:155], v[168:171], v[28:31]
	v_mfma_f32_16x16x32_bf16 v[20:23], v[160:163], v[168:171], v[20:23]
	v_mfma_f32_16x16x32_bf16 v[48:51], v[132:135], v[188:191], v[48:51]
	v_mfma_f32_16x16x32_bf16 v[40:43], v[140:143], v[188:191], v[40:43]
	v_mfma_f32_16x16x32_bf16 v[44:47], v[132:135], v[180:183], v[44:47]
	v_mfma_f32_16x16x32_bf16 v[36:39], v[140:143], v[180:183], v[36:39]
	v_mfma_f32_16x16x32_bf16 v[16:19], v[132:135], v[172:175], v[16:19]
	v_mfma_f32_16x16x32_bf16 v[8:11], v[140:143], v[172:175], v[8:11]
	v_mfma_f32_16x16x32_bf16 v[12:15], v[132:135], v[164:167], v[12:15]
	v_mfma_f32_16x16x32_bf16 v[2:5], v[140:143], v[164:167], v[4:7]
	v_mfma_f32_16x16x32_bf16 v[48:51], v[136:139], v[192:195], v[48:51]
	v_mfma_f32_16x16x32_bf16 v[40:43], v[144:147], v[192:195], v[40:43]
	v_mfma_f32_16x16x32_bf16 v[44:47], v[136:139], v[184:187], v[44:47]
	v_mfma_f32_16x16x32_bf16 v[36:39], v[144:147], v[184:187], v[36:39]
	v_mfma_f32_16x16x32_bf16 v[16:19], v[136:139], v[176:179], v[16:19]
	v_mfma_f32_16x16x32_bf16 v[8:11], v[144:147], v[176:179], v[8:11]
	v_mfma_f32_16x16x32_bf16 v[12:15], v[136:139], v[168:171], v[12:15]
	v_mfma_f32_16x16x32_bf16 v[4:7], v[144:147], v[168:171], v[2:5]
	s_setprio 0
	s_branch .LBB0_128

.LBB0_537:
	s_add_u32 s62, s60, 0xfffc0080
	s_addc_u32 s63, s61, -1
	s_add_i32 s76, 0, 0x10000
	s_cmp_eq_u32 s75, 12
	s_cselect_b32 s65, s45, s63
	s_cselect_b32 s64, s71, s62
	s_cselect_b32 s63, s43, s74
	s_cselect_b32 s62, s72, s73
	s_add_i32 s78, 0, 0x14000
	v_add_u32_e32 v102, s76, v160
	v_add_u32_e32 v158, s78, v160
	ds_read_b128 v[90:93], v102
	ds_read_b128 v[94:97], v102 offset:1024
	ds_read_b128 v[98:101], v102 offset:2048
	ds_read_b128 v[102:105], v102 offset:3072
	ds_read_b128 v[164:167], v158
	ds_read_b128 v[168:171], v158 offset:1024
	ds_read_b128 v[172:175], v158 offset:2048
	ds_read_b128 v[176:179], v158 offset:3072
	v_lshl_add_u64 v[158:159], s[60:61], 0, v[154:155]
	s_add_i32 m0, s55, 0xc000
	ds_read_b128 v[180:183], v162
	ds_read_b128 v[184:187], v162 offset:1024
	ds_read_b128 v[188:191], v162 offset:2048
	ds_read_b128 v[192:195], v162 offset:3072
	ds_read_b128 v[206:209], v162 offset:4096
	ds_read_b128 v[210:213], v162 offset:5120
	ds_read_b128 v[214:217], v162 offset:6144
	ds_read_b128 v[218:221], v162 offset:7168
	global_load_lds_dwordx4 v[158:159], off
	v_lshl_add_u64 v[158:159], s[60:61], 0, v[156:157]
	s_add_i32 m0, s55, 0xe000
	s_nop 0
	global_load_lds_dwordx4 v[158:159], off
	s_waitcnt vmcnt(8)
	s_waitcnt lgkmcnt(0)
	s_barrier
	s_setprio 1
	v_mfma_f32_16x16x32_bf16 v[142:145], v[90:93], v[180:183], v[142:145]
	v_mfma_f32_16x16x32_bf16 v[138:141], v[98:101], v[180:183], v[138:141]
	v_mfma_f32_16x16x32_bf16 v[126:129], v[90:93], v[188:191], v[126:129]
	v_mfma_f32_16x16x32_bf16 v[122:125], v[98:101], v[188:191], v[122:125]
	v_mfma_f32_16x16x32_bf16 v[110:113], v[90:93], v[206:209], v[110:113]
	v_mfma_f32_16x16x32_bf16 v[106:109], v[98:101], v[206:209], v[106:109]
	v_mfma_f32_16x16x32_bf16 v[78:81], v[90:93], v[214:217], v[78:81]
	v_mfma_f32_16x16x32_bf16 v[74:77], v[98:101], v[214:217], v[74:77]
	v_mfma_f32_16x16x32_bf16 v[142:145], v[94:97], v[184:187], v[142:145]
	v_mfma_f32_16x16x32_bf16 v[138:141], v[102:105], v[184:187], v[138:141]
	v_mfma_f32_16x16x32_bf16 v[126:129], v[94:97], v[192:195], v[126:129]
	v_mfma_f32_16x16x32_bf16 v[122:125], v[102:105], v[192:195], v[122:125]
	v_mfma_f32_16x16x32_bf16 v[110:113], v[94:97], v[210:213], v[110:113]
	v_mfma_f32_16x16x32_bf16 v[106:109], v[102:105], v[210:213], v[106:109]
	v_mfma_f32_16x16x32_bf16 v[78:81], v[94:97], v[218:221], v[78:81]
	v_mfma_f32_16x16x32_bf16 v[74:77], v[102:105], v[218:221], v[74:77]
	v_mfma_f32_16x16x32_bf16 v[134:137], v[164:167], v[180:183], v[134:137]
	v_mfma_f32_16x16x32_bf16 v[130:133], v[172:175], v[180:183], v[130:133]
	v_mfma_f32_16x16x32_bf16 v[118:121], v[164:167], v[188:191], v[118:121]
	v_mfma_f32_16x16x32_bf16 v[114:117], v[172:175], v[188:191], v[114:117]
	v_mfma_f32_16x16x32_bf16 v[86:89], v[164:167], v[206:209], v[86:89]
	v_mfma_f32_16x16x32_bf16 v[82:85], v[172:175], v[206:209], v[82:85]
	v_mfma_f32_16x16x32_bf16 v[70:73], v[164:167], v[214:217], v[70:73]
	v_mfma_f32_16x16x32_bf16 v[66:69], v[172:175], v[214:217], v[66:69]
	v_mfma_f32_16x16x32_bf16 v[134:137], v[168:171], v[184:187], v[134:137]
	v_mfma_f32_16x16x32_bf16 v[130:133], v[176:179], v[184:187], v[130:133]
	v_mfma_f32_16x16x32_bf16 v[118:121], v[168:171], v[192:195], v[118:121]
	v_mfma_f32_16x16x32_bf16 v[114:117], v[176:179], v[192:195], v[114:117]
	v_mfma_f32_16x16x32_bf16 v[86:89], v[168:171], v[210:213], v[86:89]
	v_mfma_f32_16x16x32_bf16 v[82:85], v[176:179], v[210:213], v[82:85]
	v_mfma_f32_16x16x32_bf16 v[70:73], v[168:171], v[218:221], v[70:73]
	v_mfma_f32_16x16x32_bf16 v[66:69], v[176:179], v[218:221], v[66:69]
	s_setprio 0
	s_barrier
	s_add_i32 s76, s76, s25
	v_lshl_add_u64 v[158:159], s[62:63], 0, v[0:1]
	s_mov_b32 m0, s76
	ds_read_b128 v[180:183], v162 offset:16384
	ds_read_b128 v[184:187], v162 offset:17408
	ds_read_b128 v[188:191], v162 offset:18432
	ds_read_b128 v[192:195], v162 offset:19456
	ds_read_b128 v[206:209], v162 offset:20480
	ds_read_b128 v[210:213], v162 offset:21504
	ds_read_b128 v[214:217], v162 offset:22528
	ds_read_b128 v[218:221], v162 offset:23552
	global_load_lds_dwordx4 v[158:159], off
	s_add_i32 m0, s76, 0x2000
	s_add_u32 s76, s62, 0x40000
	v_lshl_add_u64 v[222:223], s[62:63], 0, v[146:147]
	s_addc_u32 s77, s63, 0
	s_add_i32 s78, s78, s25
	global_load_lds_dwordx4 v[222:223], off
	v_lshl_add_u64 v[232:233], s[76:77], 0, v[0:1]
	s_mov_b32 m0, s78
	v_lshl_add_u64 v[234:235], s[64:65], 0, v[148:149]
	global_load_lds_dwordx4 v[232:233], off
	v_lshl_add_u64 v[232:233], s[76:77], 0, v[146:147]
	s_add_i32 m0, s78, 0x2000
	s_nop 0
	global_load_lds_dwordx4 v[232:233], off
	v_lshl_add_u64 v[232:233], s[64:65], 0, v[150:151]
	s_mov_b32 m0, s55
	s_nop 0
	global_load_lds_dwordx4 v[232:233], off
	s_mov_b32 m0, s56
	s_nop 0
	global_load_lds_dwordx4 v[234:235], off
	s_waitcnt vmcnt(8)
	s_waitcnt lgkmcnt(0)
	s_barrier
	s_setprio 1
	v_mfma_f32_16x16x32_bf16 v[62:65], v[90:93], v[180:183], v[62:65]
	v_mfma_f32_16x16x32_bf16 v[58:61], v[98:101], v[180:183], v[58:61]
	v_mfma_f32_16x16x32_bf16 v[46:49], v[90:93], v[188:191], v[46:49]
	v_mfma_f32_16x16x32_bf16 v[42:45], v[98:101], v[188:191], v[42:45]
	v_mfma_f32_16x16x32_bf16 v[30:33], v[90:93], v[206:209], v[30:33]
	v_mfma_f32_16x16x32_bf16 v[26:29], v[98:101], v[206:209], v[26:29]
	v_mfma_f32_16x16x32_bf16 v[14:17], v[90:93], v[214:217], v[14:17]
	v_mfma_f32_16x16x32_bf16 v[10:13], v[98:101], v[214:217], v[10:13]
	v_mfma_f32_16x16x32_bf16 v[62:65], v[94:97], v[184:187], v[62:65]
	v_mfma_f32_16x16x32_bf16 v[58:61], v[102:105], v[184:187], v[58:61]
	v_mfma_f32_16x16x32_bf16 v[46:49], v[94:97], v[192:195], v[46:49]
	v_mfma_f32_16x16x32_bf16 v[42:45], v[102:105], v[192:195], v[42:45]
	v_mfma_f32_16x16x32_bf16 v[30:33], v[94:97], v[210:213], v[30:33]
	v_mfma_f32_16x16x32_bf16 v[26:29], v[102:105], v[210:213], v[26:29]
	v_mfma_f32_16x16x32_bf16 v[14:17], v[94:97], v[218:221], v[14:17]
	v_mfma_f32_16x16x32_bf16 v[10:13], v[102:105], v[218:221], v[10:13]
	v_mfma_f32_16x16x32_bf16 v[54:57], v[164:167], v[180:183], v[54:57]
	v_mfma_f32_16x16x32_bf16 v[50:53], v[172:175], v[180:183], v[50:53]
	v_mfma_f32_16x16x32_bf16 v[38:41], v[164:167], v[188:191], v[38:41]
	v_mfma_f32_16x16x32_bf16 v[34:37], v[172:175], v[188:191], v[34:37]
	v_mfma_f32_16x16x32_bf16 v[22:25], v[164:167], v[206:209], v[22:25]
	v_mfma_f32_16x16x32_bf16 v[18:21], v[172:175], v[206:209], v[18:21]
	v_mfma_f32_16x16x32_bf16 v[6:9], v[164:167], v[214:217], v[6:9]
	v_mfma_f32_16x16x32_bf16 v[2:5], v[172:175], v[214:217], v[2:5]
	v_mfma_f32_16x16x32_bf16 v[54:57], v[168:171], v[184:187], v[54:57]
	v_mfma_f32_16x16x32_bf16 v[50:53], v[176:179], v[184:187], v[50:53]
	v_mfma_f32_16x16x32_bf16 v[38:41], v[168:171], v[192:195], v[38:41]
	v_mfma_f32_16x16x32_bf16 v[34:37], v[176:179], v[192:195], v[34:37]
	v_mfma_f32_16x16x32_bf16 v[22:25], v[168:171], v[210:213], v[22:25]
	v_mfma_f32_16x16x32_bf16 v[18:21], v[176:179], v[210:213], v[18:21]
	v_mfma_f32_16x16x32_bf16 v[6:9], v[168:171], v[218:221], v[6:9]
	v_mfma_f32_16x16x32_bf16 v[2:5], v[176:179], v[218:221], v[2:5]
	s_setprio 0
	s_barrier
	s_add_i32 s76, 0, 0x18000
	s_add_i32 s77, 0, 0x1c000
	v_add_u32_e32 v102, s76, v160
	v_add_u32_e32 v163, s77, v160
	ds_read_b128 v[90:93], v102
	ds_read_b128 v[94:97], v102 offset:1024
	ds_read_b128 v[98:101], v102 offset:2048
	ds_read_b128 v[102:105], v102 offset:3072
	ds_read_b128 v[164:167], v163
	ds_read_b128 v[168:171], v163 offset:1024
	ds_read_b128 v[172:175], v163 offset:2048
	ds_read_b128 v[176:179], v163 offset:3072
	s_add_u32 s64, s64, 0x40000
	s_addc_u32 s65, s65, 0
	s_mov_b32 m0, s57
	v_lshl_add_u64 v[236:237], s[64:65], 0, v[150:151]
	ds_read_b128 v[180:183], v162 offset:32768
	ds_read_b128 v[184:187], v162 offset:33792
	ds_read_b128 v[188:191], v162 offset:34816
	ds_read_b128 v[192:195], v162 offset:35840
	ds_read_b128 v[206:209], v162 offset:36864
	ds_read_b128 v[210:213], v162 offset:37888
	ds_read_b128 v[214:217], v162 offset:38912
	ds_read_b128 v[218:221], v162 offset:39936
	global_load_lds_dwordx4 v[236:237], off
	v_lshl_add_u64 v[236:237], s[64:65], 0, v[148:149]
	s_mov_b32 m0, s66
	s_nop 0
	global_load_lds_dwordx4 v[236:237], off
	s_waitcnt vmcnt(8)
	s_waitcnt lgkmcnt(0)
	s_barrier
	s_setprio 1
	v_mfma_f32_16x16x32_bf16 v[142:145], v[90:93], v[180:183], v[142:145]
	v_mfma_f32_16x16x32_bf16 v[138:141], v[98:101], v[180:183], v[138:141]
	v_mfma_f32_16x16x32_bf16 v[126:129], v[90:93], v[188:191], v[126:129]
	v_mfma_f32_16x16x32_bf16 v[122:125], v[98:101], v[188:191], v[122:125]
	v_mfma_f32_16x16x32_bf16 v[110:113], v[90:93], v[206:209], v[110:113]
	v_mfma_f32_16x16x32_bf16 v[106:109], v[98:101], v[206:209], v[106:109]
	v_mfma_f32_16x16x32_bf16 v[78:81], v[90:93], v[214:217], v[78:81]
	v_mfma_f32_16x16x32_bf16 v[74:77], v[98:101], v[214:217], v[74:77]
	v_mfma_f32_16x16x32_bf16 v[142:145], v[94:97], v[184:187], v[142:145]
	v_mfma_f32_16x16x32_bf16 v[138:141], v[102:105], v[184:187], v[138:141]
	v_mfma_f32_16x16x32_bf16 v[126:129], v[94:97], v[192:195], v[126:129]
	v_mfma_f32_16x16x32_bf16 v[122:125], v[102:105], v[192:195], v[122:125]
	v_mfma_f32_16x16x32_bf16 v[110:113], v[94:97], v[210:213], v[110:113]
	v_mfma_f32_16x16x32_bf16 v[106:109], v[102:105], v[210:213], v[106:109]
	v_mfma_f32_16x16x32_bf16 v[78:81], v[94:97], v[218:221], v[78:81]
	v_mfma_f32_16x16x32_bf16 v[74:77], v[102:105], v[218:221], v[74:77]
	v_mfma_f32_16x16x32_bf16 v[134:137], v[164:167], v[180:183], v[134:137]
	v_mfma_f32_16x16x32_bf16 v[130:133], v[172:175], v[180:183], v[130:133]
	v_mfma_f32_16x16x32_bf16 v[118:121], v[164:167], v[188:191], v[118:121]
	v_mfma_f32_16x16x32_bf16 v[114:117], v[172:175], v[188:191], v[114:117]
	v_mfma_f32_16x16x32_bf16 v[86:89], v[164:167], v[206:209], v[86:89]
	v_mfma_f32_16x16x32_bf16 v[82:85], v[172:175], v[206:209], v[82:85]
	v_mfma_f32_16x16x32_bf16 v[70:73], v[164:167], v[214:217], v[70:73]
	v_mfma_f32_16x16x32_bf16 v[66:69], v[172:175], v[214:217], v[66:69]
	v_mfma_f32_16x16x32_bf16 v[134:137], v[168:171], v[184:187], v[134:137]
	v_mfma_f32_16x16x32_bf16 v[130:133], v[176:179], v[184:187], v[130:133]
	v_mfma_f32_16x16x32_bf16 v[118:121], v[168:171], v[192:195], v[118:121]
	v_mfma_f32_16x16x32_bf16 v[114:117], v[176:179], v[192:195], v[114:117]
	v_mfma_f32_16x16x32_bf16 v[86:89], v[168:171], v[210:213], v[86:89]
	v_mfma_f32_16x16x32_bf16 v[82:85], v[176:179], v[210:213], v[82:85]
	v_mfma_f32_16x16x32_bf16 v[70:73], v[168:171], v[218:221], v[70:73]
	v_mfma_f32_16x16x32_bf16 v[66:69], v[176:179], v[218:221], v[66:69]
	s_setprio 0
	s_barrier
	s_add_i32 s64, s76, s25
	v_lshl_add_u64 v[158:159], v[158:159], 0, s[58:59]
	s_mov_b32 m0, s64
	ds_read_b128 v[180:183], v162 offset:49152
	ds_read_b128 v[184:187], v162 offset:50176
	ds_read_b128 v[188:191], v162 offset:51200
	ds_read_b128 v[192:195], v162 offset:52224
	ds_read_b128 v[206:209], v162 offset:53248
	ds_read_b128 v[210:213], v162 offset:54272
	ds_read_b128 v[214:217], v162 offset:55296
	ds_read_b128 v[218:221], v162 offset:56320
	global_load_lds_dwordx4 v[158:159], off
	s_add_i32 m0, s64, 0x2000
	s_add_u32 s62, s62, 0x40080
	v_lshl_add_u64 v[158:159], v[222:223], 0, s[58:59]
	s_addc_u32 s63, s63, 0
	s_add_i32 s64, s77, s25
	global_load_lds_dwordx4 v[158:159], off
	v_lshl_add_u64 v[158:159], s[62:63], 0, v[0:1]
	s_mov_b32 m0, s64
	s_nop 0
	global_load_lds_dwordx4 v[158:159], off
	v_lshl_add_u64 v[158:159], s[62:63], 0, v[146:147]
	s_add_i32 m0, s64, 0x2000
	s_nop 0
	global_load_lds_dwordx4 v[158:159], off
	v_lshl_add_u64 v[158:159], v[232:233], 0, s[58:59]
	s_mov_b32 m0, s30
	s_nop 0
	global_load_lds_dwordx4 v[158:159], off
	v_lshl_add_u64 v[158:159], v[234:235], 0, s[58:59]
	s_mov_b32 m0, s67
	s_nop 0
	global_load_lds_dwordx4 v[158:159], off
	s_waitcnt vmcnt(8)
	s_waitcnt lgkmcnt(0)
	s_barrier
	s_setprio 1
	v_mfma_f32_16x16x32_bf16 v[62:65], v[90:93], v[180:183], v[62:65]
	v_mfma_f32_16x16x32_bf16 v[58:61], v[98:101], v[180:183], v[58:61]
	v_mfma_f32_16x16x32_bf16 v[46:49], v[90:93], v[188:191], v[46:49]
	v_mfma_f32_16x16x32_bf16 v[42:45], v[98:101], v[188:191], v[42:45]
	v_mfma_f32_16x16x32_bf16 v[30:33], v[90:93], v[206:209], v[30:33]
	v_mfma_f32_16x16x32_bf16 v[26:29], v[98:101], v[206:209], v[26:29]
	v_mfma_f32_16x16x32_bf16 v[14:17], v[90:93], v[214:217], v[14:17]
	v_mfma_f32_16x16x32_bf16 v[10:13], v[98:101], v[214:217], v[10:13]
	v_mfma_f32_16x16x32_bf16 v[62:65], v[94:97], v[184:187], v[62:65]
	v_mfma_f32_16x16x32_bf16 v[58:61], v[102:105], v[184:187], v[58:61]
	v_mfma_f32_16x16x32_bf16 v[46:49], v[94:97], v[192:195], v[46:49]
	v_mfma_f32_16x16x32_bf16 v[42:45], v[102:105], v[192:195], v[42:45]
	v_mfma_f32_16x16x32_bf16 v[30:33], v[94:97], v[210:213], v[30:33]
	v_mfma_f32_16x16x32_bf16 v[26:29], v[102:105], v[210:213], v[26:29]
	v_mfma_f32_16x16x32_bf16 v[14:17], v[94:97], v[218:221], v[14:17]
	v_mfma_f32_16x16x32_bf16 v[10:13], v[102:105], v[218:221], v[10:13]
	v_mfma_f32_16x16x32_bf16 v[54:57], v[164:167], v[180:183], v[54:57]
	v_mfma_f32_16x16x32_bf16 v[50:53], v[172:175], v[180:183], v[50:53]
	v_mfma_f32_16x16x32_bf16 v[38:41], v[164:167], v[188:191], v[38:41]
	v_mfma_f32_16x16x32_bf16 v[34:37], v[172:175], v[188:191], v[34:37]
	v_mfma_f32_16x16x32_bf16 v[22:25], v[164:167], v[206:209], v[22:25]
	v_mfma_f32_16x16x32_bf16 v[18:21], v[172:175], v[206:209], v[18:21]
	v_mfma_f32_16x16x32_bf16 v[6:9], v[164:167], v[214:217], v[6:9]
	v_mfma_f32_16x16x32_bf16 v[2:5], v[172:175], v[214:217], v[2:5]
	v_mfma_f32_16x16x32_bf16 v[54:57], v[168:171], v[184:187], v[54:57]
	v_mfma_f32_16x16x32_bf16 v[50:53], v[176:179], v[184:187], v[50:53]
	v_mfma_f32_16x16x32_bf16 v[38:41], v[168:171], v[192:195], v[38:41]
	v_mfma_f32_16x16x32_bf16 v[34:37], v[176:179], v[192:195], v[34:37]
	v_mfma_f32_16x16x32_bf16 v[22:25], v[168:171], v[210:213], v[22:25]
	v_mfma_f32_16x16x32_bf16 v[18:21], v[176:179], v[210:213], v[18:21]
	v_mfma_f32_16x16x32_bf16 v[6:9], v[168:171], v[218:221], v[6:9]
	v_mfma_f32_16x16x32_bf16 v[2:5], v[176:179], v[218:221], v[2:5]
	s_setprio 0
	s_barrier
	s_add_i32 s75, s75, 2
	s_add_u32 s60, s60, 0x100
	s_addc_u32 s61, s61, 0
	s_add_u32 s73, s73, 0x100
	s_addc_u32 s74, s74, 0
	s_cmp_gt_u32 s75, 13
	s_cbranch_scc0 .LBB0_537
	s_and_b64 vcc, exec, s[40:41]
	s_cbranch_vccz .LBB0_540
	s_barrier

.LBB0_616:
	s_add_u32 s62, s60, 0x100
	s_addc_u32 s63, s61, 0
	s_add_i32 s78, 0, 0x10000
	s_cmp_eq_u32 s77, 4
	s_cselect_b32 s67, s43, s63
	s_cselect_b32 s66, s42, s62
	v_add_u32_e32 v0, s78, v161
	s_cselect_b32 s65, s51, s76
	s_cselect_b32 s64, s50, s47
	s_add_i32 s79, 0, 0x14000
	ds_read_b128 v[132:135], v0
	ds_read_b128 v[136:139], v0 offset:1024
	ds_read_b128 v[154:157], v0 offset:2048
	ds_read_b128 v[164:167], v0 offset:3072
	v_add_u32_e32 v0, s79, v161
	ds_read_b128 v[168:171], v0
	ds_read_b128 v[172:175], v0 offset:1024
	ds_read_b128 v[176:179], v0 offset:2048
	ds_read_b128 v[180:183], v0 offset:3072
	v_lshl_add_u64 v[2:3], s[60:61], 0, v[150:151]
	s_add_i32 m0, s30, 0xc000
	ds_read_b128 v[184:187], v163
	ds_read_b128 v[188:191], v163 offset:1024
	ds_read_b128 v[192:195], v163 offset:2048
	ds_read_b128 v[206:209], v163 offset:3072
	ds_read_b128 v[210:213], v163 offset:4096
	ds_read_b128 v[214:217], v163 offset:5120
	ds_read_b128 v[218:221], v163 offset:6144
	ds_read_b128 v[232:235], v163 offset:7168
	global_load_lds_dwordx4 v[2:3], off
	v_lshl_add_u64 v[2:3], s[60:61], 0, v[152:153]
	s_add_i32 m0, s30, 0xe000
	s_nop 0
	global_load_lds_dwordx4 v[2:3], off
	s_waitcnt vmcnt(8)
	s_waitcnt lgkmcnt(0)
	s_barrier
	s_setprio 1
	v_mfma_f32_16x16x32_bf16 v[128:131], v[132:135], v[184:187], v[128:131]
	v_mfma_f32_16x16x32_bf16 v[124:127], v[154:157], v[184:187], v[124:127]
	v_mfma_f32_16x16x32_bf16 v[120:123], v[132:135], v[192:195], v[120:123]
	v_mfma_f32_16x16x32_bf16 v[116:119], v[154:157], v[192:195], v[116:119]
	v_mfma_f32_16x16x32_bf16 v[112:115], v[132:135], v[210:213], v[112:115]
	v_mfma_f32_16x16x32_bf16 v[108:111], v[154:157], v[210:213], v[108:111]
	v_mfma_f32_16x16x32_bf16 v[104:107], v[132:135], v[218:221], v[104:107]
	v_mfma_f32_16x16x32_bf16 v[100:103], v[154:157], v[218:221], v[100:103]
	v_mfma_f32_16x16x32_bf16 v[128:131], v[136:139], v[188:191], v[128:131]
	v_mfma_f32_16x16x32_bf16 v[124:127], v[164:167], v[188:191], v[124:127]
	v_mfma_f32_16x16x32_bf16 v[120:123], v[136:139], v[206:209], v[120:123]
	v_mfma_f32_16x16x32_bf16 v[116:119], v[164:167], v[206:209], v[116:119]
	v_mfma_f32_16x16x32_bf16 v[112:115], v[136:139], v[214:217], v[112:115]
	v_mfma_f32_16x16x32_bf16 v[108:111], v[164:167], v[214:217], v[108:111]
	v_mfma_f32_16x16x32_bf16 v[104:107], v[136:139], v[232:235], v[104:107]
	v_mfma_f32_16x16x32_bf16 v[100:103], v[164:167], v[232:235], v[100:103]
	v_mfma_f32_16x16x32_bf16 v[96:99], v[168:171], v[184:187], v[96:99]
	v_mfma_f32_16x16x32_bf16 v[92:95], v[176:179], v[184:187], v[92:95]
	v_mfma_f32_16x16x32_bf16 v[88:91], v[168:171], v[192:195], v[88:91]
	v_mfma_f32_16x16x32_bf16 v[84:87], v[176:179], v[192:195], v[84:87]
	v_mfma_f32_16x16x32_bf16 v[80:83], v[168:171], v[210:213], v[80:83]
	v_mfma_f32_16x16x32_bf16 v[76:79], v[176:179], v[210:213], v[76:79]
	v_mfma_f32_16x16x32_bf16 v[72:75], v[168:171], v[218:221], v[72:75]
	v_mfma_f32_16x16x32_bf16 v[68:71], v[176:179], v[218:221], v[68:71]
	v_mfma_f32_16x16x32_bf16 v[96:99], v[172:175], v[188:191], v[96:99]
	v_mfma_f32_16x16x32_bf16 v[92:95], v[180:183], v[188:191], v[92:95]
	v_mfma_f32_16x16x32_bf16 v[88:91], v[172:175], v[206:209], v[88:91]
	v_mfma_f32_16x16x32_bf16 v[84:87], v[180:183], v[206:209], v[84:87]
	v_mfma_f32_16x16x32_bf16 v[80:83], v[172:175], v[214:217], v[80:83]
	v_mfma_f32_16x16x32_bf16 v[76:79], v[180:183], v[214:217], v[76:79]
	v_mfma_f32_16x16x32_bf16 v[72:75], v[172:175], v[232:235], v[72:75]
	v_mfma_f32_16x16x32_bf16 v[68:71], v[180:183], v[232:235], v[68:71]
	s_setprio 0
	s_barrier
	s_add_i32 s60, s78, s25
	v_lshl_add_u64 v[158:159], s[64:65], 0, v[144:145]
	s_mov_b32 m0, s60
	ds_read_b128 v[184:187], v163 offset:16384
	ds_read_b128 v[188:191], v163 offset:17408
	ds_read_b128 v[192:195], v163 offset:18432
	ds_read_b128 v[206:209], v163 offset:19456
	ds_read_b128 v[210:213], v163 offset:20480
	ds_read_b128 v[214:217], v163 offset:21504
	ds_read_b128 v[218:221], v163 offset:22528
	ds_read_b128 v[232:235], v163 offset:23552
	global_load_lds_dwordx4 v[158:159], off
	s_add_i32 m0, s60, 0x2000
	s_add_u32 s60, s64, 0x60000
	v_lshl_add_u64 v[222:223], s[64:65], 0, v[140:141]
	s_addc_u32 s61, s65, 0
	s_add_i32 s78, s79, s25
	global_load_lds_dwordx4 v[222:223], off
	v_lshl_add_u64 v[2:3], s[60:61], 0, v[144:145]
	s_mov_b32 m0, s78
	v_lshl_add_u64 v[236:237], s[66:67], 0, v[146:147]
	global_load_lds_dwordx4 v[2:3], off
	v_lshl_add_u64 v[2:3], s[60:61], 0, v[140:141]
	s_add_i32 m0, s78, 0x2000
	v_lshl_add_u64 v[238:239], s[66:67], 0, v[142:143]
	global_load_lds_dwordx4 v[2:3], off
	s_mov_b32 m0, s30
	s_nop 0
	global_load_lds_dwordx4 v[236:237], off
	s_mov_b32 m0, s55
	s_nop 0
	global_load_lds_dwordx4 v[238:239], off
	s_waitcnt vmcnt(8)
	s_waitcnt lgkmcnt(0)
	s_barrier
	s_setprio 1
	v_mfma_f32_16x16x32_bf16 v[64:67], v[132:135], v[184:187], v[64:67]
	v_mfma_f32_16x16x32_bf16 v[60:63], v[154:157], v[184:187], v[60:63]
	v_mfma_f32_16x16x32_bf16 v[56:59], v[132:135], v[192:195], v[56:59]
	v_mfma_f32_16x16x32_bf16 v[52:55], v[154:157], v[192:195], v[52:55]
	v_mfma_f32_16x16x32_bf16 v[48:51], v[132:135], v[210:213], v[48:51]
	v_mfma_f32_16x16x32_bf16 v[44:47], v[154:157], v[210:213], v[44:47]
	v_mfma_f32_16x16x32_bf16 v[40:43], v[132:135], v[218:221], v[40:43]
	v_mfma_f32_16x16x32_bf16 v[36:39], v[154:157], v[218:221], v[36:39]
	v_mfma_f32_16x16x32_bf16 v[64:67], v[136:139], v[188:191], v[64:67]
	v_mfma_f32_16x16x32_bf16 v[60:63], v[164:167], v[188:191], v[60:63]
	v_mfma_f32_16x16x32_bf16 v[56:59], v[136:139], v[206:209], v[56:59]
	v_mfma_f32_16x16x32_bf16 v[52:55], v[164:167], v[206:209], v[52:55]
	v_mfma_f32_16x16x32_bf16 v[48:51], v[136:139], v[214:217], v[48:51]
	v_mfma_f32_16x16x32_bf16 v[44:47], v[164:167], v[214:217], v[44:47]
	v_mfma_f32_16x16x32_bf16 v[40:43], v[136:139], v[232:235], v[40:43]
	v_mfma_f32_16x16x32_bf16 v[36:39], v[164:167], v[232:235], v[36:39]
	v_mfma_f32_16x16x32_bf16 v[32:35], v[168:171], v[184:187], v[32:35]
	v_mfma_f32_16x16x32_bf16 v[28:31], v[176:179], v[184:187], v[28:31]
	v_mfma_f32_16x16x32_bf16 v[24:27], v[168:171], v[192:195], v[24:27]
	v_mfma_f32_16x16x32_bf16 v[20:23], v[176:179], v[192:195], v[20:23]
	v_mfma_f32_16x16x32_bf16 v[16:19], v[168:171], v[210:213], v[16:19]
	v_mfma_f32_16x16x32_bf16 v[12:15], v[176:179], v[210:213], v[12:15]
	v_mfma_f32_16x16x32_bf16 v[8:11], v[168:171], v[218:221], v[8:11]
	v_mfma_f32_16x16x32_bf16 v[2:5], v[176:179], v[218:221], v[4:7]
	v_mfma_f32_16x16x32_bf16 v[32:35], v[172:175], v[188:191], v[32:35]
	v_mfma_f32_16x16x32_bf16 v[28:31], v[180:183], v[188:191], v[28:31]
	v_mfma_f32_16x16x32_bf16 v[24:27], v[172:175], v[206:209], v[24:27]
	v_mfma_f32_16x16x32_bf16 v[20:23], v[180:183], v[206:209], v[20:23]
	v_mfma_f32_16x16x32_bf16 v[16:19], v[172:175], v[214:217], v[16:19]
	v_mfma_f32_16x16x32_bf16 v[12:15], v[180:183], v[214:217], v[12:15]
	v_mfma_f32_16x16x32_bf16 v[8:11], v[172:175], v[232:235], v[8:11]
	v_mfma_f32_16x16x32_bf16 v[2:5], v[180:183], v[232:235], v[2:5]
	s_setprio 0
	s_barrier
	s_add_i32 s78, 0, 0x18000
	v_add_u32_e32 v0, s78, v161
	s_add_i32 s79, 0, 0x1c000
	ds_read_b128 v[132:135], v0
	ds_read_b128 v[136:139], v0 offset:1024
	ds_read_b128 v[154:157], v0 offset:2048
	ds_read_b128 v[164:167], v0 offset:3072
	v_add_u32_e32 v0, s79, v161
	ds_read_b128 v[168:171], v0
	ds_read_b128 v[172:175], v0 offset:1024
	ds_read_b128 v[176:179], v0 offset:2048
	ds_read_b128 v[180:183], v0 offset:3072
	s_add_u32 s60, s66, 0x60000
	s_addc_u32 s61, s67, 0
	s_mov_b32 m0, s56
	v_lshl_add_u64 v[6:7], s[60:61], 0, v[146:147]
	ds_read_b128 v[184:187], v163 offset:32768
	ds_read_b128 v[188:191], v163 offset:33792
	ds_read_b128 v[192:195], v163 offset:34816
	ds_read_b128 v[206:209], v163 offset:35840
	ds_read_b128 v[210:213], v163 offset:36864
	ds_read_b128 v[214:217], v163 offset:37888
	ds_read_b128 v[218:221], v163 offset:38912
	ds_read_b128 v[232:235], v163 offset:39936
	global_load_lds_dwordx4 v[6:7], off
	v_lshl_add_u64 v[6:7], s[60:61], 0, v[142:143]
	s_mov_b32 m0, s57
	s_nop 0
	global_load_lds_dwordx4 v[6:7], off
	s_waitcnt vmcnt(8)
	s_waitcnt lgkmcnt(0)
	s_barrier
	s_setprio 1
	v_mfma_f32_16x16x32_bf16 v[128:131], v[132:135], v[184:187], v[128:131]
	v_mfma_f32_16x16x32_bf16 v[124:127], v[154:157], v[184:187], v[124:127]
	v_mfma_f32_16x16x32_bf16 v[120:123], v[132:135], v[192:195], v[120:123]
	v_mfma_f32_16x16x32_bf16 v[116:119], v[154:157], v[192:195], v[116:119]
	v_mfma_f32_16x16x32_bf16 v[112:115], v[132:135], v[210:213], v[112:115]
	v_mfma_f32_16x16x32_bf16 v[108:111], v[154:157], v[210:213], v[108:111]
	v_mfma_f32_16x16x32_bf16 v[104:107], v[132:135], v[218:221], v[104:107]
	v_mfma_f32_16x16x32_bf16 v[100:103], v[154:157], v[218:221], v[100:103]
	v_mfma_f32_16x16x32_bf16 v[128:131], v[136:139], v[188:191], v[128:131]
	v_mfma_f32_16x16x32_bf16 v[124:127], v[164:167], v[188:191], v[124:127]
	v_mfma_f32_16x16x32_bf16 v[120:123], v[136:139], v[206:209], v[120:123]
	v_mfma_f32_16x16x32_bf16 v[116:119], v[164:167], v[206:209], v[116:119]
	v_mfma_f32_16x16x32_bf16 v[112:115], v[136:139], v[214:217], v[112:115]
	v_mfma_f32_16x16x32_bf16 v[108:111], v[164:167], v[214:217], v[108:111]
	v_mfma_f32_16x16x32_bf16 v[104:107], v[136:139], v[232:235], v[104:107]
	v_mfma_f32_16x16x32_bf16 v[100:103], v[164:167], v[232:235], v[100:103]
	v_mfma_f32_16x16x32_bf16 v[96:99], v[168:171], v[184:187], v[96:99]
	v_mfma_f32_16x16x32_bf16 v[92:95], v[176:179], v[184:187], v[92:95]
	v_mfma_f32_16x16x32_bf16 v[88:91], v[168:171], v[192:195], v[88:91]
	v_mfma_f32_16x16x32_bf16 v[84:87], v[176:179], v[192:195], v[84:87]
	v_mfma_f32_16x16x32_bf16 v[80:83], v[168:171], v[210:213], v[80:83]
	v_mfma_f32_16x16x32_bf16 v[76:79], v[176:179], v[210:213], v[76:79]
	v_mfma_f32_16x16x32_bf16 v[72:75], v[168:171], v[218:221], v[72:75]
	v_mfma_f32_16x16x32_bf16 v[68:71], v[176:179], v[218:221], v[68:71]
	v_mfma_f32_16x16x32_bf16 v[96:99], v[172:175], v[188:191], v[96:99]
	v_mfma_f32_16x16x32_bf16 v[92:95], v[180:183], v[188:191], v[92:95]
	v_mfma_f32_16x16x32_bf16 v[88:91], v[172:175], v[206:209], v[88:91]
	v_mfma_f32_16x16x32_bf16 v[84:87], v[180:183], v[206:209], v[84:87]
	v_mfma_f32_16x16x32_bf16 v[80:83], v[172:175], v[214:217], v[80:83]
	v_mfma_f32_16x16x32_bf16 v[76:79], v[180:183], v[214:217], v[76:79]
	v_mfma_f32_16x16x32_bf16 v[72:75], v[172:175], v[232:235], v[72:75]
	v_mfma_f32_16x16x32_bf16 v[68:71], v[180:183], v[232:235], v[68:71]
	s_setprio 0
	s_barrier
	s_add_i32 s60, s78, s25
	v_lshl_add_u64 v[6:7], v[158:159], 0, s[58:59]
	s_mov_b32 m0, s60
	ds_read_b128 v[184:187], v163 offset:49152
	ds_read_b128 v[188:191], v163 offset:50176
	ds_read_b128 v[192:195], v163 offset:51200
	ds_read_b128 v[206:209], v163 offset:52224
	ds_read_b128 v[210:213], v163 offset:53248
	ds_read_b128 v[214:217], v163 offset:54272
	ds_read_b128 v[218:221], v163 offset:55296
	ds_read_b128 v[232:235], v163 offset:56320
	global_load_lds_dwordx4 v[6:7], off
	s_add_i32 m0, s60, 0x2000
	s_add_u32 s60, s64, 0x60080
	v_lshl_add_u64 v[6:7], v[222:223], 0, s[58:59]
	s_addc_u32 s61, s65, 0
	s_add_i32 s64, s79, s25
	global_load_lds_dwordx4 v[6:7], off
	v_lshl_add_u64 v[6:7], s[60:61], 0, v[144:145]
	s_mov_b32 m0, s64
	s_nop 0
	global_load_lds_dwordx4 v[6:7], off
	v_lshl_add_u64 v[6:7], s[60:61], 0, v[140:141]
	s_add_i32 m0, s64, 0x2000
	s_nop 0
	global_load_lds_dwordx4 v[6:7], off
	v_lshl_add_u64 v[6:7], v[236:237], 0, s[58:59]
	s_mov_b32 m0, s68
	s_nop 0
	global_load_lds_dwordx4 v[6:7], off
	v_lshl_add_u64 v[6:7], v[238:239], 0, s[58:59]
	s_mov_b32 m0, s69
	s_nop 0
	global_load_lds_dwordx4 v[6:7], off
	s_waitcnt vmcnt(8)
	s_waitcnt lgkmcnt(0)
	s_barrier
	s_setprio 1
	v_mfma_f32_16x16x32_bf16 v[64:67], v[132:135], v[184:187], v[64:67]
	v_mfma_f32_16x16x32_bf16 v[60:63], v[154:157], v[184:187], v[60:63]
	v_mfma_f32_16x16x32_bf16 v[56:59], v[132:135], v[192:195], v[56:59]
	v_mfma_f32_16x16x32_bf16 v[52:55], v[154:157], v[192:195], v[52:55]
	v_mfma_f32_16x16x32_bf16 v[48:51], v[132:135], v[210:213], v[48:51]
	v_mfma_f32_16x16x32_bf16 v[44:47], v[154:157], v[210:213], v[44:47]
	v_mfma_f32_16x16x32_bf16 v[40:43], v[132:135], v[218:221], v[40:43]
	v_mfma_f32_16x16x32_bf16 v[36:39], v[154:157], v[218:221], v[36:39]
	v_mfma_f32_16x16x32_bf16 v[64:67], v[136:139], v[188:191], v[64:67]
	v_mfma_f32_16x16x32_bf16 v[60:63], v[164:167], v[188:191], v[60:63]
	v_mfma_f32_16x16x32_bf16 v[56:59], v[136:139], v[206:209], v[56:59]
	v_mfma_f32_16x16x32_bf16 v[52:55], v[164:167], v[206:209], v[52:55]
	v_mfma_f32_16x16x32_bf16 v[48:51], v[136:139], v[214:217], v[48:51]
	v_mfma_f32_16x16x32_bf16 v[44:47], v[164:167], v[214:217], v[44:47]
	v_mfma_f32_16x16x32_bf16 v[40:43], v[136:139], v[232:235], v[40:43]
	v_mfma_f32_16x16x32_bf16 v[36:39], v[164:167], v[232:235], v[36:39]
	v_mfma_f32_16x16x32_bf16 v[32:35], v[168:171], v[184:187], v[32:35]
	v_mfma_f32_16x16x32_bf16 v[28:31], v[176:179], v[184:187], v[28:31]
	v_mfma_f32_16x16x32_bf16 v[24:27], v[168:171], v[192:195], v[24:27]
	v_mfma_f32_16x16x32_bf16 v[20:23], v[176:179], v[192:195], v[20:23]
	v_mfma_f32_16x16x32_bf16 v[16:19], v[168:171], v[210:213], v[16:19]
	v_mfma_f32_16x16x32_bf16 v[12:15], v[176:179], v[210:213], v[12:15]
	v_mfma_f32_16x16x32_bf16 v[6:9], v[168:171], v[218:221], v[8:11]
	v_mfma_f32_16x16x32_bf16 v[2:5], v[176:179], v[218:221], v[2:5]
	v_mfma_f32_16x16x32_bf16 v[32:35], v[172:175], v[188:191], v[32:35]
	v_mfma_f32_16x16x32_bf16 v[28:31], v[180:183], v[188:191], v[28:31]
	v_mfma_f32_16x16x32_bf16 v[24:27], v[172:175], v[206:209], v[24:27]
	v_mfma_f32_16x16x32_bf16 v[20:23], v[180:183], v[206:209], v[20:23]
	v_mfma_f32_16x16x32_bf16 v[16:19], v[172:175], v[214:217], v[16:19]
	v_mfma_f32_16x16x32_bf16 v[12:15], v[180:183], v[214:217], v[12:15]
	v_mfma_f32_16x16x32_bf16 v[8:11], v[172:175], v[232:235], v[6:9]
	v_mfma_f32_16x16x32_bf16 v[4:7], v[180:183], v[232:235], v[2:5]
	s_setprio 0
	s_barrier
	s_add_i32 s77, s77, 2
	s_add_u32 s47, s47, 0x100
	s_addc_u32 s76, s76, 0
	s_cmp_gt_u32 s77, 5
	s_mov_b64 s[60:61], s[62:63]
	s_cbranch_scc0 .LBB0_616
	s_and_b64 vcc, exec, s[44:45]
	s_cbranch_vccz .LBB0_619
	s_barrier

.LBB0_697:
	s_add_u32 s66, s64, 0xfffc0080
	s_addc_u32 s67, s65, -1
	s_add_i32 s81, 0, 0x10000
	s_cmp_eq_u32 s80, 12
	s_cselect_b32 s69, s51, s67
	s_cselect_b32 s68, s76, s66
	s_cselect_b32 s67, s47, s79
	s_cselect_b32 s66, s77, s78
	s_add_i32 s84, 0, 0x14000
	v_add_u32_e32 v156, s81, v145
	v_add_u32_e32 v172, s84, v145
	ds_read_b128 v[140:143], v156
	ds_read_b128 v[148:151], v156 offset:1024
	ds_read_b128 v[152:155], v156 offset:2048
	ds_read_b128 v[156:159], v156 offset:3072
	ds_read_b128 v[160:163], v172
	ds_read_b128 v[164:167], v172 offset:1024
	ds_read_b128 v[168:171], v172 offset:2048
	ds_read_b128 v[172:175], v172 offset:3072
	v_lshl_add_u64 v[218:219], s[64:65], 0, v[136:137]
	s_add_i32 m0, s55, 0xc000
	ds_read_b128 v[176:179], v147
	ds_read_b128 v[180:183], v147 offset:1024
	ds_read_b128 v[184:187], v147 offset:2048
	ds_read_b128 v[188:191], v147 offset:3072
	ds_read_b128 v[192:195], v147 offset:4096
	ds_read_b128 v[206:209], v147 offset:5120
	ds_read_b128 v[210:213], v147 offset:6144
	ds_read_b128 v[214:217], v147 offset:7168
	global_load_lds_dwordx4 v[218:219], off
	v_lshl_add_u64 v[218:219], s[64:65], 0, v[138:139]
	s_add_i32 m0, s55, 0xe000
	s_nop 0
	global_load_lds_dwordx4 v[218:219], off
	s_waitcnt vmcnt(8)
	s_waitcnt lgkmcnt(0)
	s_barrier
	s_setprio 1
	v_mfma_f32_16x16x32_bf16 v[126:129], v[140:143], v[176:179], v[126:129]
	v_mfma_f32_16x16x32_bf16 v[122:125], v[152:155], v[176:179], v[122:125]
	v_mfma_f32_16x16x32_bf16 v[110:113], v[140:143], v[184:187], v[110:113]
	v_mfma_f32_16x16x32_bf16 v[106:109], v[152:155], v[184:187], v[106:109]
	v_mfma_f32_16x16x32_bf16 v[94:97], v[140:143], v[192:195], v[94:97]
	v_mfma_f32_16x16x32_bf16 v[90:93], v[152:155], v[192:195], v[90:93]
	v_mfma_f32_16x16x32_bf16 v[78:81], v[140:143], v[210:213], v[78:81]
	v_mfma_f32_16x16x32_bf16 v[74:77], v[152:155], v[210:213], v[74:77]
	v_mfma_f32_16x16x32_bf16 v[126:129], v[148:151], v[180:183], v[126:129]
	v_mfma_f32_16x16x32_bf16 v[122:125], v[156:159], v[180:183], v[122:125]
	v_mfma_f32_16x16x32_bf16 v[110:113], v[148:151], v[188:191], v[110:113]
	v_mfma_f32_16x16x32_bf16 v[106:109], v[156:159], v[188:191], v[106:109]
	v_mfma_f32_16x16x32_bf16 v[94:97], v[148:151], v[206:209], v[94:97]
	v_mfma_f32_16x16x32_bf16 v[90:93], v[156:159], v[206:209], v[90:93]
	v_mfma_f32_16x16x32_bf16 v[78:81], v[148:151], v[214:217], v[78:81]
	v_mfma_f32_16x16x32_bf16 v[74:77], v[156:159], v[214:217], v[74:77]
	v_mfma_f32_16x16x32_bf16 v[118:121], v[160:163], v[176:179], v[118:121]
	v_mfma_f32_16x16x32_bf16 v[114:117], v[168:171], v[176:179], v[114:117]
	v_mfma_f32_16x16x32_bf16 v[102:105], v[160:163], v[184:187], v[102:105]
	v_mfma_f32_16x16x32_bf16 v[98:101], v[168:171], v[184:187], v[98:101]
	v_mfma_f32_16x16x32_bf16 v[86:89], v[160:163], v[192:195], v[86:89]
	v_mfma_f32_16x16x32_bf16 v[82:85], v[168:171], v[192:195], v[82:85]
	v_mfma_f32_16x16x32_bf16 v[70:73], v[160:163], v[210:213], v[70:73]
	v_mfma_f32_16x16x32_bf16 v[66:69], v[168:171], v[210:213], v[66:69]
	v_mfma_f32_16x16x32_bf16 v[118:121], v[164:167], v[180:183], v[118:121]
	v_mfma_f32_16x16x32_bf16 v[114:117], v[172:175], v[180:183], v[114:117]
	v_mfma_f32_16x16x32_bf16 v[102:105], v[164:167], v[188:191], v[102:105]
	v_mfma_f32_16x16x32_bf16 v[98:101], v[172:175], v[188:191], v[98:101]
	v_mfma_f32_16x16x32_bf16 v[86:89], v[164:167], v[206:209], v[86:89]
	v_mfma_f32_16x16x32_bf16 v[82:85], v[172:175], v[206:209], v[82:85]
	v_mfma_f32_16x16x32_bf16 v[70:73], v[164:167], v[214:217], v[70:73]
	v_mfma_f32_16x16x32_bf16 v[66:69], v[172:175], v[214:217], v[66:69]
	s_setprio 0
	s_barrier
	s_add_i32 s81, s81, s25
	v_lshl_add_u64 v[218:219], s[66:67], 0, v[0:1]
	s_mov_b32 m0, s81
	ds_read_b128 v[176:179], v147 offset:16384
	ds_read_b128 v[180:183], v147 offset:17408
	ds_read_b128 v[184:187], v147 offset:18432
	ds_read_b128 v[188:191], v147 offset:19456
	ds_read_b128 v[192:195], v147 offset:20480
	ds_read_b128 v[206:209], v147 offset:21504
	ds_read_b128 v[210:213], v147 offset:22528
	ds_read_b128 v[214:217], v147 offset:23552
	global_load_lds_dwordx4 v[218:219], off
	s_add_i32 m0, s81, 0x2000
	s_add_u32 s82, s66, 0x40000
	v_lshl_add_u64 v[220:221], s[66:67], 0, v[130:131]
	s_addc_u32 s83, s67, 0
	s_add_i32 s81, s84, s25
	global_load_lds_dwordx4 v[220:221], off
	v_lshl_add_u64 v[222:223], s[82:83], 0, v[0:1]
	s_mov_b32 m0, s81
	v_lshl_add_u64 v[232:233], s[68:69], 0, v[132:133]
	global_load_lds_dwordx4 v[222:223], off
	v_lshl_add_u64 v[222:223], s[82:83], 0, v[130:131]
	s_add_i32 m0, s81, 0x2000
	s_nop 0
	global_load_lds_dwordx4 v[222:223], off
	v_lshl_add_u64 v[222:223], s[68:69], 0, v[134:135]
	s_mov_b32 m0, s55
	s_nop 0
	global_load_lds_dwordx4 v[222:223], off
	s_mov_b32 m0, s56
	s_nop 0
	global_load_lds_dwordx4 v[232:233], off
	s_waitcnt vmcnt(8)
	s_waitcnt lgkmcnt(0)
	s_barrier
	s_setprio 1
	v_mfma_f32_16x16x32_bf16 v[62:65], v[140:143], v[176:179], v[62:65]
	v_mfma_f32_16x16x32_bf16 v[58:61], v[152:155], v[176:179], v[58:61]
	v_mfma_f32_16x16x32_bf16 v[46:49], v[140:143], v[184:187], v[46:49]
	v_mfma_f32_16x16x32_bf16 v[42:45], v[152:155], v[184:187], v[42:45]
	v_mfma_f32_16x16x32_bf16 v[30:33], v[140:143], v[192:195], v[30:33]
	v_mfma_f32_16x16x32_bf16 v[26:29], v[152:155], v[192:195], v[26:29]
	v_mfma_f32_16x16x32_bf16 v[14:17], v[140:143], v[210:213], v[14:17]
	v_mfma_f32_16x16x32_bf16 v[10:13], v[152:155], v[210:213], v[10:13]
	v_mfma_f32_16x16x32_bf16 v[62:65], v[148:151], v[180:183], v[62:65]
	v_mfma_f32_16x16x32_bf16 v[58:61], v[156:159], v[180:183], v[58:61]
	v_mfma_f32_16x16x32_bf16 v[46:49], v[148:151], v[188:191], v[46:49]
	v_mfma_f32_16x16x32_bf16 v[42:45], v[156:159], v[188:191], v[42:45]
	v_mfma_f32_16x16x32_bf16 v[30:33], v[148:151], v[206:209], v[30:33]
	v_mfma_f32_16x16x32_bf16 v[26:29], v[156:159], v[206:209], v[26:29]
	v_mfma_f32_16x16x32_bf16 v[14:17], v[148:151], v[214:217], v[14:17]
	v_mfma_f32_16x16x32_bf16 v[10:13], v[156:159], v[214:217], v[10:13]
	v_mfma_f32_16x16x32_bf16 v[54:57], v[160:163], v[176:179], v[54:57]
	v_mfma_f32_16x16x32_bf16 v[50:53], v[168:171], v[176:179], v[50:53]
	v_mfma_f32_16x16x32_bf16 v[38:41], v[160:163], v[184:187], v[38:41]
	v_mfma_f32_16x16x32_bf16 v[34:37], v[168:171], v[184:187], v[34:37]
	v_mfma_f32_16x16x32_bf16 v[22:25], v[160:163], v[192:195], v[22:25]
	v_mfma_f32_16x16x32_bf16 v[18:21], v[168:171], v[192:195], v[18:21]
	v_mfma_f32_16x16x32_bf16 v[6:9], v[160:163], v[210:213], v[6:9]
	v_mfma_f32_16x16x32_bf16 v[2:5], v[168:171], v[210:213], v[2:5]
	v_mfma_f32_16x16x32_bf16 v[54:57], v[164:167], v[180:183], v[54:57]
	v_mfma_f32_16x16x32_bf16 v[50:53], v[172:175], v[180:183], v[50:53]
	v_mfma_f32_16x16x32_bf16 v[38:41], v[164:167], v[188:191], v[38:41]
	v_mfma_f32_16x16x32_bf16 v[34:37], v[172:175], v[188:191], v[34:37]
	v_mfma_f32_16x16x32_bf16 v[22:25], v[164:167], v[206:209], v[22:25]
	v_mfma_f32_16x16x32_bf16 v[18:21], v[172:175], v[206:209], v[18:21]
	v_mfma_f32_16x16x32_bf16 v[6:9], v[164:167], v[214:217], v[6:9]
	v_mfma_f32_16x16x32_bf16 v[2:5], v[172:175], v[214:217], v[2:5]
	s_setprio 0
	s_barrier
	s_add_i32 s81, 0, 0x18000
	s_add_i32 s82, 0, 0x1c000
	v_add_u32_e32 v156, s81, v145
	v_add_u32_e32 v172, s82, v145
	ds_read_b128 v[140:143], v156
	ds_read_b128 v[148:151], v156 offset:1024
	ds_read_b128 v[152:155], v156 offset:2048
	ds_read_b128 v[156:159], v156 offset:3072
	ds_read_b128 v[160:163], v172
	ds_read_b128 v[164:167], v172 offset:1024
	ds_read_b128 v[168:171], v172 offset:2048
	ds_read_b128 v[172:175], v172 offset:3072
	s_add_u32 s68, s68, 0x40000
	s_addc_u32 s69, s69, 0
	s_mov_b32 m0, s57
	v_lshl_add_u64 v[234:235], s[68:69], 0, v[134:135]
	ds_read_b128 v[176:179], v147 offset:32768
	ds_read_b128 v[180:183], v147 offset:33792
	ds_read_b128 v[184:187], v147 offset:34816
	ds_read_b128 v[188:191], v147 offset:35840
	ds_read_b128 v[192:195], v147 offset:36864
	ds_read_b128 v[206:209], v147 offset:37888
	ds_read_b128 v[210:213], v147 offset:38912
	ds_read_b128 v[214:217], v147 offset:39936
	global_load_lds_dwordx4 v[234:235], off
	v_lshl_add_u64 v[234:235], s[68:69], 0, v[132:133]
	s_mov_b32 m0, s70
	s_nop 0
	global_load_lds_dwordx4 v[234:235], off
	s_waitcnt vmcnt(8)
	s_waitcnt lgkmcnt(0)
	s_barrier
	s_setprio 1
	v_mfma_f32_16x16x32_bf16 v[126:129], v[140:143], v[176:179], v[126:129]
	v_mfma_f32_16x16x32_bf16 v[122:125], v[152:155], v[176:179], v[122:125]
	v_mfma_f32_16x16x32_bf16 v[110:113], v[140:143], v[184:187], v[110:113]
	v_mfma_f32_16x16x32_bf16 v[106:109], v[152:155], v[184:187], v[106:109]
	v_mfma_f32_16x16x32_bf16 v[94:97], v[140:143], v[192:195], v[94:97]
	v_mfma_f32_16x16x32_bf16 v[90:93], v[152:155], v[192:195], v[90:93]
	v_mfma_f32_16x16x32_bf16 v[78:81], v[140:143], v[210:213], v[78:81]
	v_mfma_f32_16x16x32_bf16 v[74:77], v[152:155], v[210:213], v[74:77]
	v_mfma_f32_16x16x32_bf16 v[126:129], v[148:151], v[180:183], v[126:129]
	v_mfma_f32_16x16x32_bf16 v[122:125], v[156:159], v[180:183], v[122:125]
	v_mfma_f32_16x16x32_bf16 v[110:113], v[148:151], v[188:191], v[110:113]
	v_mfma_f32_16x16x32_bf16 v[106:109], v[156:159], v[188:191], v[106:109]
	v_mfma_f32_16x16x32_bf16 v[94:97], v[148:151], v[206:209], v[94:97]
	v_mfma_f32_16x16x32_bf16 v[90:93], v[156:159], v[206:209], v[90:93]
	v_mfma_f32_16x16x32_bf16 v[78:81], v[148:151], v[214:217], v[78:81]
	v_mfma_f32_16x16x32_bf16 v[74:77], v[156:159], v[214:217], v[74:77]
	v_mfma_f32_16x16x32_bf16 v[118:121], v[160:163], v[176:179], v[118:121]
	v_mfma_f32_16x16x32_bf16 v[114:117], v[168:171], v[176:179], v[114:117]
	v_mfma_f32_16x16x32_bf16 v[102:105], v[160:163], v[184:187], v[102:105]
	v_mfma_f32_16x16x32_bf16 v[98:101], v[168:171], v[184:187], v[98:101]
	v_mfma_f32_16x16x32_bf16 v[86:89], v[160:163], v[192:195], v[86:89]
	v_mfma_f32_16x16x32_bf16 v[82:85], v[168:171], v[192:195], v[82:85]
	v_mfma_f32_16x16x32_bf16 v[70:73], v[160:163], v[210:213], v[70:73]
	v_mfma_f32_16x16x32_bf16 v[66:69], v[168:171], v[210:213], v[66:69]
	v_mfma_f32_16x16x32_bf16 v[118:121], v[164:167], v[180:183], v[118:121]
	v_mfma_f32_16x16x32_bf16 v[114:117], v[172:175], v[180:183], v[114:117]
	v_mfma_f32_16x16x32_bf16 v[102:105], v[164:167], v[188:191], v[102:105]
	v_mfma_f32_16x16x32_bf16 v[98:101], v[172:175], v[188:191], v[98:101]
	v_mfma_f32_16x16x32_bf16 v[86:89], v[164:167], v[206:209], v[86:89]
	v_mfma_f32_16x16x32_bf16 v[82:85], v[172:175], v[206:209], v[82:85]
	v_mfma_f32_16x16x32_bf16 v[70:73], v[164:167], v[214:217], v[70:73]
	v_mfma_f32_16x16x32_bf16 v[66:69], v[172:175], v[214:217], v[66:69]
	s_setprio 0
	s_barrier
	s_add_i32 s68, s81, s25
	v_lshl_add_u64 v[218:219], v[218:219], 0, s[58:59]
	s_mov_b32 m0, s68
	ds_read_b128 v[176:179], v147 offset:49152
	ds_read_b128 v[180:183], v147 offset:50176
	ds_read_b128 v[184:187], v147 offset:51200
	ds_read_b128 v[188:191], v147 offset:52224
	ds_read_b128 v[192:195], v147 offset:53248
	ds_read_b128 v[206:209], v147 offset:54272
	ds_read_b128 v[210:213], v147 offset:55296
	ds_read_b128 v[214:217], v147 offset:56320
	global_load_lds_dwordx4 v[218:219], off
	s_add_i32 m0, s68, 0x2000
	s_add_u32 s66, s66, 0x40080
	v_lshl_add_u64 v[218:219], v[220:221], 0, s[58:59]
	s_addc_u32 s67, s67, 0
	s_add_i32 s68, s82, s25
	global_load_lds_dwordx4 v[218:219], off
	v_lshl_add_u64 v[218:219], s[66:67], 0, v[0:1]
	s_mov_b32 m0, s68
	s_nop 0
	global_load_lds_dwordx4 v[218:219], off
	v_lshl_add_u64 v[218:219], s[66:67], 0, v[130:131]
	s_add_i32 m0, s68, 0x2000
	s_nop 0
	global_load_lds_dwordx4 v[218:219], off
	v_lshl_add_u64 v[218:219], v[222:223], 0, s[58:59]
	s_mov_b32 m0, s72
	s_nop 0
	global_load_lds_dwordx4 v[218:219], off
	v_lshl_add_u64 v[218:219], v[232:233], 0, s[58:59]
	s_mov_b32 m0, s73
	s_nop 0
	global_load_lds_dwordx4 v[218:219], off
	s_waitcnt vmcnt(8)
	s_waitcnt lgkmcnt(0)
	s_barrier
	s_setprio 1
	v_mfma_f32_16x16x32_bf16 v[62:65], v[140:143], v[176:179], v[62:65]
	v_mfma_f32_16x16x32_bf16 v[58:61], v[152:155], v[176:179], v[58:61]
	v_mfma_f32_16x16x32_bf16 v[46:49], v[140:143], v[184:187], v[46:49]
	v_mfma_f32_16x16x32_bf16 v[42:45], v[152:155], v[184:187], v[42:45]
	v_mfma_f32_16x16x32_bf16 v[30:33], v[140:143], v[192:195], v[30:33]
	v_mfma_f32_16x16x32_bf16 v[26:29], v[152:155], v[192:195], v[26:29]
	v_mfma_f32_16x16x32_bf16 v[14:17], v[140:143], v[210:213], v[14:17]
	v_mfma_f32_16x16x32_bf16 v[10:13], v[152:155], v[210:213], v[10:13]
	v_mfma_f32_16x16x32_bf16 v[62:65], v[148:151], v[180:183], v[62:65]
	v_mfma_f32_16x16x32_bf16 v[58:61], v[156:159], v[180:183], v[58:61]
	v_mfma_f32_16x16x32_bf16 v[46:49], v[148:151], v[188:191], v[46:49]
	v_mfma_f32_16x16x32_bf16 v[42:45], v[156:159], v[188:191], v[42:45]
	v_mfma_f32_16x16x32_bf16 v[30:33], v[148:151], v[206:209], v[30:33]
	v_mfma_f32_16x16x32_bf16 v[26:29], v[156:159], v[206:209], v[26:29]
	v_mfma_f32_16x16x32_bf16 v[14:17], v[148:151], v[214:217], v[14:17]
	v_mfma_f32_16x16x32_bf16 v[10:13], v[156:159], v[214:217], v[10:13]
	v_mfma_f32_16x16x32_bf16 v[54:57], v[160:163], v[176:179], v[54:57]
	v_mfma_f32_16x16x32_bf16 v[50:53], v[168:171], v[176:179], v[50:53]
	v_mfma_f32_16x16x32_bf16 v[38:41], v[160:163], v[184:187], v[38:41]
	v_mfma_f32_16x16x32_bf16 v[34:37], v[168:171], v[184:187], v[34:37]
	v_mfma_f32_16x16x32_bf16 v[22:25], v[160:163], v[192:195], v[22:25]
	v_mfma_f32_16x16x32_bf16 v[18:21], v[168:171], v[192:195], v[18:21]
	v_mfma_f32_16x16x32_bf16 v[6:9], v[160:163], v[210:213], v[6:9]
	v_mfma_f32_16x16x32_bf16 v[2:5], v[168:171], v[210:213], v[2:5]
	v_mfma_f32_16x16x32_bf16 v[54:57], v[164:167], v[180:183], v[54:57]
	v_mfma_f32_16x16x32_bf16 v[50:53], v[172:175], v[180:183], v[50:53]
	v_mfma_f32_16x16x32_bf16 v[38:41], v[164:167], v[188:191], v[38:41]
	v_mfma_f32_16x16x32_bf16 v[34:37], v[172:175], v[188:191], v[34:37]
	v_mfma_f32_16x16x32_bf16 v[22:25], v[164:167], v[206:209], v[22:25]
	v_mfma_f32_16x16x32_bf16 v[18:21], v[172:175], v[206:209], v[18:21]
	v_mfma_f32_16x16x32_bf16 v[6:9], v[164:167], v[214:217], v[6:9]
	v_mfma_f32_16x16x32_bf16 v[2:5], v[172:175], v[214:217], v[2:5]
	s_setprio 0
	s_barrier
	s_add_i32 s80, s80, 2
	s_add_u32 s64, s64, 0x100
	s_addc_u32 s65, s65, 0
	s_add_u32 s78, s78, 0x100
	s_addc_u32 s79, s79, 0
	s_cmp_gt_u32 s80, 13
	s_cbranch_scc0 .LBB0_697
	s_and_b64 vcc, exec, s[44:45]
	s_cbranch_vccz .LBB0_700
	s_barrier
